# gate/up GEMM: SwiGLU epilogue bias + rowss loads prefetched at the top of the last K iteration (epilogue starts without a load round trip)
# speedup vs baseline: 1.0099x; 1.0099x over previous
; #define PG8_STAGE(bufoff, gbase, voff) do { _Pragma("unroll") for (int _i = 0; _i < 2; ++_i) \
;         __builtin_amdgcn_global_load_lds((const unsigned*)((const char*)(gbase) + (voff)[_i]), (PG8_LAS unsigned*)(lds + (bufoff) + ldsw + _i * 8192), 16, 0, 0); } while (0)
; #define PG8_LDA(dst, b, h) do { _Pragma("unroll") for (int m = 0; m < 4; ++m) _Pragma("unroll") for (int k = 0; k < 2; ++k) dst[m][k] = *(const PG8_LAS bf16x8*)(lds + PG8_SA(b, h) + aoff + m * 2048 + k * 1024); } while (0)
; #define PG8_WAIT_V(n) asm volatile("s_waitcnt vmcnt(" #n ")" ::: "memory")
;     __device__ __forceinline__ void operator()(const f32x4 (&acc)[2][2][4][2], const Unit& u, int wr, int wc, int fr, int fq) const {
;     ...
;         const float* bp = bias + (size_t)((u.pm * BM) >> 14) * 5632 + u.pn * BM + wc * 32 + 8 * fq;
;         f32x4 bz[2][2];
; #pragma unroll
;         for (int bj = 0; bj < 2; ++bj)
; #pragma unroll
;             for (int n = 0; n < 2; ++n) bz[bj][n] = *(const f32x4*)(bp + bj * HALF + 4 * n);
; #pragma unroll
;         for (int ai = 0; ai < 2; ++ai)
; #pragma unroll
;             for (int m = 0; m < 4; ++m) {
;                 float o[8]; const float rv = rsqrtf(rowss[row0 + ai * HALF + m * 16] * (1.0f / 1024.0f) + 1e-6f);
; template <class Epi, class Sched, bool ALIGN_EPI = false, bool SP2 = false, bool F16 = false>
; __device__ __forceinline__ void gemm_phase(PG8_LAS unsigned char* lds, const Gemm g, const Sched& S, const Epi& E) {
;     ...
;             const bool last = (t == nt - 2);
;             const char* a1 = cA + (size_t)(t + 1) * kstep;
;             const char* a2 = last ? nA : cA + (size_t)(t + 2) * kstep; const char* b2 = last ? nB : cB + (size_t)(t + 2) * kstep;
;             const char* a3 = a2 + kstep; const char* b3 = b2 + kstep;
;             if (last && has_next) S.a_ready(nxt);
;             if constexpr (SP2) {
;             PG8_LDB(B0, 0, 0); PG8_LDB(B1, 0, 1); PG8_SCHED; PG8_LDA(At, 0, 0); PG8_STAGE(PG8_SA(1, 1), a1 + hstep, voffA);
;             PG8_WAIT_V(8); PG8_WAIT_L(0); PG8_BAR; PG8_MMA(0, 0, At, B0); PG8_MMA(0, 1, At, B1); PG8_BAR; PG8_SCHED;
;             PG8_LDA(At, 0, 1); PG8_STAGE(PG8_SB(0, 0), b2, voffB); PG8_STAGE(PG8_SB(0, 1), b2 + hstep, voffB); PG8_STAGE(PG8_SA(0, 0), a2, voffA);
;             PG8_WAIT_V(8); PG8_WAIT_L(0); PG8_BAR; PG8_MMA(1, 0, At, B0); PG8_MMA(1, 1, At, B1); PG8_BAR; PG8_SCHED;
.LBB0_904:
	s_add_u32 s56, s54, 0xfffc0080
	s_addc_u32 s57, s55, -1
	s_add_i32 s62, 0, 0x10000
	s_cmp_eq_u32 s61, 12
	s_cselect_b32 s59, s4, s57
	s_cselect_b32 s58, s5, s56
	s_cselect_b32 s57, s37, s60
	s_cselect_b32 s56, s47, s49
	s_add_i32 s64, 0, 0x14000
	s_cmp_eq_u32 s61, 12
	s_cbranch_scc0 .Lgu_nopf
	s_ashr_i32 s98, s34, 6
	s_mul_hi_i32 s99, s98, 0x5800
	s_mulk_i32 s98, 0x5800
	s_add_u32 s98, s14, s98
	s_addc_u32 s99, s15, s99
	s_lshl_b32 s100, s31, 8
	s_ashr_i32 s101, s100, 31
	s_lshl_b64 s[100:101], s[100:101], 2
	s_add_u32 s98, s98, s100
	s_addc_u32 s99, s99, s101
	s_add_u32 s98, s98, s30
	s_addc_u32 s99, s99, 0
	v_lshl_add_u32 v238, s34, 8, v162
	v_ashrrev_i32_e32 v239, 31, v238
	v_lshl_add_u64 v[240:241], v[238:239], 2, s[42:43]
	global_load_dword v147, v[240:241], off
	global_load_dword v149, v[240:241], off offset:64
	global_load_dword v151, v[240:241], off offset:128
	global_load_dword v153, v[240:241], off offset:192
	global_load_dword v155, v[240:241], off offset:512
	global_load_dword v167, v[240:241], off offset:576
	global_load_dword v173, v[240:241], off offset:640
	global_load_dword v250, v[240:241], off offset:704
	global_load_dwordx4 v[242:245], v166, s[98:99] offset:16
	global_load_dwordx4 v[246:249], v166, s[98:99]
	global_load_dwordx4 v[174:177], v166, s[98:99] offset:528
	global_load_dwordx4 v[238:241], v166, s[98:99] offset:512
.Lgu_nopf:
	ds_read_b128 v[32:35], v172
	ds_read_b128 v[36:39], v172 offset:1024
	ds_read_b128 v[40:43], v172 offset:2048
	ds_read_b128 v[44:47], v172 offset:3072
	ds_read_b128 v[156:159], v172 offset:16384
	ds_read_b128 v[168:171], v172 offset:17408
	ds_read_b128 v[186:189], v172 offset:18432
	ds_read_b128 v[190:193], v172 offset:19456
	s_add_i32 m0, s9, 0xc000
	ds_read_b128 v[194:197], v165
	ds_read_b128 v[198:201], v165 offset:1024
	ds_read_b128 v[202:205], v165 offset:2048
	ds_read_b128 v[206:209], v165 offset:3072
	ds_read_b128 v[210:213], v165 offset:4096
	ds_read_b128 v[214:217], v165 offset:5120
	ds_read_b128 v[218:221], v165 offset:6144
	ds_read_b128 v[222:225], v165 offset:7168
	global_load_lds_dwordx4 v152, s[54:55]
	s_add_i32 m0, s9, 0xe000
	s_nop 0
	global_load_lds_dwordx4 v154, s[54:55]
	s_waitcnt vmcnt(8)
	s_waitcnt lgkmcnt(0)
	s_barrier
	s_setprio 1
	s_waitcnt lgkmcnt(0)
	v_mfma_f32_16x16x32_f16 v[142:145], v[32:35], v[194:197], v[142:145]
	v_mfma_f32_16x16x32_f16 v[138:141], v[40:43], v[194:197], v[138:141]
	v_mfma_f32_16x16x32_f16 v[124:127], v[32:35], v[202:205], v[124:127]
	v_mfma_f32_16x16x32_f16 v[120:123], v[40:43], v[202:205], v[120:123]
	v_mfma_f32_16x16x32_f16 v[108:111], v[32:35], v[210:213], v[108:111]
	v_mfma_f32_16x16x32_f16 v[104:107], v[40:43], v[210:213], v[104:107]
	v_mfma_f32_16x16x32_f16 v[92:95], v[32:35], v[218:221], v[92:95]
	v_mfma_f32_16x16x32_f16 v[88:91], v[40:43], v[218:221], v[88:91]
	v_mfma_f32_16x16x32_f16 v[142:145], v[36:39], v[198:201], v[142:145]
	v_mfma_f32_16x16x32_f16 v[138:141], v[44:47], v[198:201], v[138:141]
	v_mfma_f32_16x16x32_f16 v[124:127], v[36:39], v[206:209], v[124:127]
	v_mfma_f32_16x16x32_f16 v[120:123], v[44:47], v[206:209], v[120:123]
	v_mfma_f32_16x16x32_f16 v[108:111], v[36:39], v[214:217], v[108:111]
	v_mfma_f32_16x16x32_f16 v[104:107], v[44:47], v[214:217], v[104:107]
	v_mfma_f32_16x16x32_f16 v[92:95], v[36:39], v[222:225], v[92:95]
	v_mfma_f32_16x16x32_f16 v[88:91], v[44:47], v[222:225], v[88:91]
	v_mfma_f32_16x16x32_f16 v[134:137], v[156:159], v[194:197], v[134:137]
	v_mfma_f32_16x16x32_f16 v[130:133], v[186:189], v[194:197], v[130:133]
	v_mfma_f32_16x16x32_f16 v[116:119], v[156:159], v[202:205], v[116:119]
	v_mfma_f32_16x16x32_f16 v[112:115], v[186:189], v[202:205], v[112:115]
	v_mfma_f32_16x16x32_f16 v[100:103], v[156:159], v[210:213], v[100:103]
	v_mfma_f32_16x16x32_f16 v[96:99], v[186:189], v[210:213], v[96:99]
	v_mfma_f32_16x16x32_f16 v[84:87], v[156:159], v[218:221], v[84:87]
	v_mfma_f32_16x16x32_f16 v[80:83], v[186:189], v[218:221], v[80:83]
	v_mfma_f32_16x16x32_f16 v[134:137], v[168:171], v[198:201], v[134:137]
	v_mfma_f32_16x16x32_f16 v[130:133], v[190:193], v[198:201], v[130:133]
	v_mfma_f32_16x16x32_f16 v[116:119], v[168:171], v[206:209], v[116:119]
	v_mfma_f32_16x16x32_f16 v[112:115], v[190:193], v[206:209], v[112:115]
	v_mfma_f32_16x16x32_f16 v[100:103], v[168:171], v[214:217], v[100:103]
	v_mfma_f32_16x16x32_f16 v[96:99], v[190:193], v[214:217], v[96:99]
	v_mfma_f32_16x16x32_f16 v[84:87], v[168:171], v[222:225], v[84:87]
	v_mfma_f32_16x16x32_f16 v[80:83], v[190:193], v[222:225], v[80:83]
	s_setprio 0
	s_barrier
	s_add_u32 s98, s56, s16
	s_addc_u32 s99, s57, s17
	s_add_u32 s100, s58, s16
	s_addc_u32 s101, s59, s17
	s_add_i32 s62, s62, s8
	s_mov_b32 m0, s62
	ds_read_b128 v[194:197], v165 offset:16384
	ds_read_b128 v[198:201], v165 offset:17408
	ds_read_b128 v[202:205], v165 offset:18432
	ds_read_b128 v[206:209], v165 offset:19456
	ds_read_b128 v[210:213], v165 offset:20480
	ds_read_b128 v[214:217], v165 offset:21504
	ds_read_b128 v[218:221], v165 offset:22528
	ds_read_b128 v[222:225], v165 offset:23552
	global_load_lds_dwordx4 v128, s[56:57]
	s_add_i32 m0, s62, 0x2000
	s_add_u32 s62, s56, 0x40000
	s_addc_u32 s63, s57, 0
	s_add_i32 s64, s64, s8
	global_load_lds_dwordx4 v146, s[56:57]
	s_mov_b32 m0, s64
	s_nop 0
	global_load_lds_dwordx4 v128, s[62:63]
	s_add_i32 m0, s64, 0x2000
	s_nop 0
	global_load_lds_dwordx4 v146, s[62:63]
	s_mov_b32 m0, s9
	s_nop 0
	global_load_lds_dwordx4 v150, s[58:59]
	s_mov_b32 m0, s10
	s_nop 0
	global_load_lds_dwordx4 v148, s[58:59]
	s_waitcnt vmcnt(8)
	s_waitcnt lgkmcnt(0)
	s_barrier
; #define PG8_STAGE(bufoff, gbase, voff) do { _Pragma("unroll") for (int _i = 0; _i < 2; ++_i) \
;         __builtin_amdgcn_global_load_lds((const unsigned*)((const char*)(gbase) + (voff)[_i]), (PG8_LAS unsigned*)(lds + (bufoff) + ldsw + _i * 8192), 16, 0, 0); } while (0)
; #define PG8_LDA(dst, b, h) do { _Pragma("unroll") for (int m = 0; m < 4; ++m) _Pragma("unroll") for (int k = 0; k < 2; ++k) dst[m][k] = *(const PG8_LAS bf16x8*)(lds + PG8_SA(b, h) + aoff + m * 2048 + k * 1024); } while (0)
; #define PG8_LDB(dst, b, h) do { _Pragma("unroll") for (int n = 0; n < 2; ++n) _Pragma("unroll") for (int k = 0; k < 2; ++k) dst[n][k] = *(const PG8_LAS bf16x8*)(lds + PG8_SB(b, h) + boff + n * 2048 + k * 1024); } while (0)
; #define PG8_MMA(ai, bj, At, Bt) do { __builtin_amdgcn_s_setprio(1); _Pragma("unroll") for (int m = 0; m < 4; ++m) _Pragma("unroll") for (int n = 0; n < 2; ++n) _Pragma("unroll") for (int k = 0; k < 2; ++k) \
;         acc[ai][bj][m][n] = mma16<F16>(Bt[n][k], At[m][k], acc[ai][bj][m][n]); __builtin_amdgcn_s_setprio(0); } while (0)
; #define PG8_WAIT_V(n) asm volatile("s_waitcnt vmcnt(" #n ")" ::: "memory")
; #define PG8_WAIT_L(n) asm volatile("s_waitcnt lgkmcnt(" #n ")" ::: "memory")
; #define PG8_BAR __builtin_amdgcn_s_barrier()
; #define PG8_SCHED __builtin_amdgcn_sched_barrier(0)
; template <class Epi, class Sched, bool ALIGN_EPI = false, bool SP2 = false, bool F16 = false>
; __device__ __forceinline__ void gemm_phase(PG8_LAS unsigned char* lds, const Gemm g, const Sched& S, const Epi& E) {
;     ...
;             PG8_WAIT_V(8); PG8_WAIT_L(0); PG8_BAR; PG8_MMA(1, 0, At, B0); PG8_MMA(1, 1, At, B1); PG8_BAR; PG8_SCHED;
;             PG8_LDB(B0, 1, 0); PG8_LDB(B1, 1, 1); PG8_SCHED; PG8_LDA(At, 1, 0); PG8_STAGE(PG8_SA(0, 1), a2 + hstep, voffA);
;             PG8_WAIT_V(8); PG8_WAIT_L(0); PG8_BAR; PG8_MMA(0, 0, At, B0); PG8_MMA(0, 1, At, B1); PG8_BAR; PG8_SCHED;
	s_setprio 1
	s_waitcnt lgkmcnt(0)
	v_mfma_f32_16x16x32_f16 v[76:79], v[32:35], v[194:197], v[76:79]
	v_mfma_f32_16x16x32_f16 v[72:75], v[40:43], v[194:197], v[72:75]
	v_mfma_f32_16x16x32_f16 v[60:63], v[32:35], v[202:205], v[60:63]
	v_mfma_f32_16x16x32_f16 v[56:59], v[40:43], v[202:205], v[56:59]
	v_mfma_f32_16x16x32_f16 v[28:31], v[32:35], v[210:213], v[28:31]
	v_mfma_f32_16x16x32_f16 v[24:27], v[40:43], v[210:213], v[24:27]
	v_mfma_f32_16x16x32_f16 v[12:15], v[32:35], v[218:221], v[12:15]
	v_mfma_f32_16x16x32_f16 v[8:11], v[40:43], v[218:221], v[8:11]
	v_mfma_f32_16x16x32_f16 v[76:79], v[36:39], v[198:201], v[76:79]
	v_mfma_f32_16x16x32_f16 v[72:75], v[44:47], v[198:201], v[72:75]
	v_mfma_f32_16x16x32_f16 v[60:63], v[36:39], v[206:209], v[60:63]
	v_mfma_f32_16x16x32_f16 v[56:59], v[44:47], v[206:209], v[56:59]
	v_mfma_f32_16x16x32_f16 v[28:31], v[36:39], v[214:217], v[28:31]
	v_mfma_f32_16x16x32_f16 v[24:27], v[44:47], v[214:217], v[24:27]
	v_mfma_f32_16x16x32_f16 v[12:15], v[36:39], v[222:225], v[12:15]
	v_mfma_f32_16x16x32_f16 v[8:11], v[44:47], v[222:225], v[8:11]
	v_mfma_f32_16x16x32_f16 v[20:23], v[156:159], v[210:213], v[20:23]
	v_mfma_f32_16x16x32_f16 v[16:19], v[186:189], v[210:213], v[16:19]
	v_mfma_f32_16x16x32_f16 v[4:7], v[156:159], v[218:221], v[4:7]
	v_mfma_f32_16x16x32_f16 v[0:3], v[186:189], v[218:221], v[0:3]
	v_mfma_f32_16x16x32_f16 v[32:35], v[156:159], v[194:197], v[68:71]
	v_mfma_f32_16x16x32_f16 v[36:39], v[186:189], v[194:197], v[64:67]
	v_mfma_f32_16x16x32_f16 v[40:43], v[156:159], v[202:205], v[52:55]
	v_mfma_f32_16x16x32_f16 v[44:47], v[186:189], v[202:205], v[48:51]
	v_mfma_f32_16x16x32_f16 v[20:23], v[168:171], v[214:217], v[20:23]
	v_mfma_f32_16x16x32_f16 v[16:19], v[190:193], v[214:217], v[16:19]
	v_mfma_f32_16x16x32_f16 v[4:7], v[168:171], v[222:225], v[4:7]
	v_mfma_f32_16x16x32_f16 v[0:3], v[190:193], v[222:225], v[0:3]
	v_mfma_f32_16x16x32_f16 v[32:35], v[168:171], v[198:201], v[32:35]
	v_mfma_f32_16x16x32_f16 v[36:39], v[190:193], v[198:201], v[36:39]
	v_mfma_f32_16x16x32_f16 v[40:43], v[168:171], v[206:209], v[40:43]
	v_mfma_f32_16x16x32_f16 v[44:47], v[190:193], v[206:209], v[44:47]
	s_setprio 0
	s_barrier
	s_add_i32 s62, 0, 0x18000
	s_add_i32 s63, 0, 0x1c000
	ds_read_b128 v[48:51], v172 offset:32768
	ds_read_b128 v[52:55], v172 offset:33792
	ds_read_b128 v[64:67], v172 offset:34816
	ds_read_b128 v[68:71], v172 offset:35840
	ds_read_b128 v[156:159], v172 offset:49152
	ds_read_b128 v[168:171], v172 offset:50176
	ds_read_b128 v[186:189], v172 offset:51200
	ds_read_b128 v[190:193], v172 offset:52224
	s_add_u32 s58, s58, 0x40000
	s_addc_u32 s59, s59, 0
	s_mov_b32 m0, s11
	ds_read_b128 v[194:197], v165 offset:32768
	ds_read_b128 v[198:201], v165 offset:33792
	ds_read_b128 v[202:205], v165 offset:34816
	ds_read_b128 v[206:209], v165 offset:35840
	ds_read_b128 v[210:213], v165 offset:36864
	ds_read_b128 v[214:217], v165 offset:37888
	ds_read_b128 v[218:221], v165 offset:38912
	ds_read_b128 v[222:225], v165 offset:39936
	global_load_lds_dwordx4 v150, s[58:59]
	s_mov_b32 m0, s13
	s_nop 0
	global_load_lds_dwordx4 v148, s[58:59]
	s_waitcnt vmcnt(8)
	s_waitcnt lgkmcnt(0)
	s_barrier
	s_setprio 1
	s_waitcnt lgkmcnt(0)
	v_mfma_f32_16x16x32_f16 v[142:145], v[48:51], v[194:197], v[142:145]
	v_mfma_f32_16x16x32_f16 v[138:141], v[64:67], v[194:197], v[138:141]
	v_mfma_f32_16x16x32_f16 v[124:127], v[48:51], v[202:205], v[124:127]
	v_mfma_f32_16x16x32_f16 v[120:123], v[64:67], v[202:205], v[120:123]
	v_mfma_f32_16x16x32_f16 v[108:111], v[48:51], v[210:213], v[108:111]
	v_mfma_f32_16x16x32_f16 v[104:107], v[64:67], v[210:213], v[104:107]
	v_mfma_f32_16x16x32_f16 v[92:95], v[48:51], v[218:221], v[92:95]
	v_mfma_f32_16x16x32_f16 v[88:91], v[64:67], v[218:221], v[88:91]
	v_mfma_f32_16x16x32_f16 v[142:145], v[52:55], v[198:201], v[142:145]
	v_mfma_f32_16x16x32_f16 v[138:141], v[68:71], v[198:201], v[138:141]
	v_mfma_f32_16x16x32_f16 v[124:127], v[52:55], v[206:209], v[124:127]
	v_mfma_f32_16x16x32_f16 v[120:123], v[68:71], v[206:209], v[120:123]
	v_mfma_f32_16x16x32_f16 v[108:111], v[52:55], v[214:217], v[108:111]
	v_mfma_f32_16x16x32_f16 v[104:107], v[68:71], v[214:217], v[104:107]
	v_mfma_f32_16x16x32_f16 v[92:95], v[52:55], v[222:225], v[92:95]
	v_mfma_f32_16x16x32_f16 v[88:91], v[68:71], v[222:225], v[88:91]
	v_mfma_f32_16x16x32_f16 v[134:137], v[156:159], v[194:197], v[134:137]
	v_mfma_f32_16x16x32_f16 v[130:133], v[186:189], v[194:197], v[130:133]
	v_mfma_f32_16x16x32_f16 v[116:119], v[156:159], v[202:205], v[116:119]
	v_mfma_f32_16x16x32_f16 v[112:115], v[186:189], v[202:205], v[112:115]
	v_mfma_f32_16x16x32_f16 v[100:103], v[156:159], v[210:213], v[100:103]
	v_mfma_f32_16x16x32_f16 v[96:99], v[186:189], v[210:213], v[96:99]
	v_mfma_f32_16x16x32_f16 v[84:87], v[156:159], v[218:221], v[84:87]
	v_mfma_f32_16x16x32_f16 v[80:83], v[186:189], v[218:221], v[80:83]
	v_mfma_f32_16x16x32_f16 v[134:137], v[168:171], v[198:201], v[134:137]
	v_mfma_f32_16x16x32_f16 v[130:133], v[190:193], v[198:201], v[130:133]
	v_mfma_f32_16x16x32_f16 v[116:119], v[168:171], v[206:209], v[116:119]
	v_mfma_f32_16x16x32_f16 v[112:115], v[190:193], v[206:209], v[112:115]
	v_mfma_f32_16x16x32_f16 v[100:103], v[168:171], v[214:217], v[100:103]
	v_mfma_f32_16x16x32_f16 v[96:99], v[190:193], v[214:217], v[96:99]
	v_mfma_f32_16x16x32_f16 v[84:87], v[168:171], v[222:225], v[84:87]
	v_mfma_f32_16x16x32_f16 v[80:83], v[190:193], v[222:225], v[80:83]
	s_setprio 0
	s_barrier
;     __device__ __forceinline__ void operator()(const f32x4 (&acc)[2][2][4][2], const Unit& u, int wr, int wc, int fr, int fq) const {
;         const int row0 = u.pm * BM + wr * 64 + fr; const int col0 = u.pn * HALF + wc * 32 + 8 * fq;
;         const float* bp = bias + (size_t)((u.pm * BM) >> 14) * 5632 + u.pn * BM + wc * 32 + 8 * fq;
;         f32x4 bz[2][2];
; #pragma unroll
;         for (int bj = 0; bj < 2; ++bj)
; #pragma unroll
;             for (int n = 0; n < 2; ++n) bz[bj][n] = *(const f32x4*)(bp + bj * HALF + 4 * n);
; #pragma unroll
; template <class Epi, class Sched, bool ALIGN_EPI = false, bool SP2 = false, bool F16 = false>
; __device__ __forceinline__ void gemm_phase(PG8_LAS unsigned char* lds, const Gemm g, const Sched& S, const Epi& E) {
;     ...
;             PG8_LDA(At, 1, 1); PG8_STAGE(PG8_SB(1, 0), b3, voffB); PG8_STAGE(PG8_SB(1, 1), b3 + hstep, voffB); PG8_STAGE(PG8_SA(1, 0), a3, voffA);
;             PG8_WAIT_V(8); PG8_WAIT_L(0); PG8_BAR; PG8_MMA(1, 0, At, B0); PG8_MMA(1, 1, At, B1); PG8_BAR; PG8_SCHED;
;             } else {
;             PG8_LDB(B0, 0, 0); PG8_SCHED; PG8_LDA(At, 0, 0); PG8_STAGE(PG8_SA(1, 1), a1 + hstep, voffA);
;             PG8_WAIT_L(8); PG8_BAR; PG8_WAIT_L(0); PG8_MMA(0, 0, At, B0); PG8_BAR; PG8_SCHED;
;             PG8_LDB(B1, 0, 1); PG8_STAGE(PG8_SB(0, 0), b2, voffB);
;             PG8_BAR; PG8_WAIT_L(0); PG8_MMA(0, 1, At, B1); PG8_BAR;
;             PG8_LDA(At, 0, 1); PG8_STAGE(PG8_SA(0, 0), a2, voffA);
;             PG8_BAR; PG8_WAIT_L(0); PG8_MMA(1, 0, At, B0); PG8_BAR; PG8_SCHED;
;             PG8_STAGE(PG8_SB(0, 1), b2 + hstep, voffB);
;             PG8_WAIT_V(6); PG8_BAR; PG8_MMA(1, 1, At, B1); PG8_BAR;
;             PG8_LDB(B0, 1, 0); PG8_SCHED; PG8_LDA(At, 1, 0); PG8_STAGE(PG8_SA(0, 1), a2 + hstep, voffA);
;             PG8_WAIT_L(8); PG8_BAR; PG8_WAIT_L(0); PG8_MMA(0, 0, At, B0); PG8_BAR; PG8_SCHED;
;             PG8_LDB(B1, 1, 1); PG8_STAGE(PG8_SB(1, 0), b3, voffB);
;             PG8_BAR; PG8_WAIT_L(0); PG8_MMA(0, 1, At, B1); PG8_BAR;
;             PG8_LDA(At, 1, 1); PG8_STAGE(PG8_SA(1, 0), a3, voffA);
;             PG8_BAR; PG8_WAIT_L(0); PG8_MMA(1, 0, At, B0); PG8_BAR; PG8_SCHED;
;             PG8_STAGE(PG8_SB(1, 1), b3 + hstep, voffB);
;             PG8_WAIT_V(6); PG8_BAR; PG8_MMA(1, 1, At, B1); PG8_BAR;
;             }
;         }
;         if constexpr (ALIGN_EPI) { if (wr == 0) PG8_BAR; }
	s_add_i32 s58, s62, s8
	s_mov_b32 m0, s58
	ds_read_b128 v[194:197], v165 offset:49152
	ds_read_b128 v[198:201], v165 offset:50176
	ds_read_b128 v[202:205], v165 offset:51200
	ds_read_b128 v[206:209], v165 offset:52224
	ds_read_b128 v[210:213], v165 offset:53248
	ds_read_b128 v[214:217], v165 offset:54272
	ds_read_b128 v[218:221], v165 offset:55296
	ds_read_b128 v[222:225], v165 offset:56320
	global_load_lds_dwordx4 v128, s[98:99]
	s_add_i32 m0, s58, 0x2000
	s_add_u32 s56, s56, 0x40080
	s_addc_u32 s57, s57, 0
	s_add_i32 s58, s63, s8
	global_load_lds_dwordx4 v146, s[98:99]
	s_mov_b32 m0, s58
	s_nop 0
	global_load_lds_dwordx4 v128, s[56:57]
	s_add_i32 m0, s58, 0x2000
	s_nop 0
	global_load_lds_dwordx4 v146, s[56:57]
	s_mov_b32 m0, s20
	s_nop 0
	global_load_lds_dwordx4 v150, s[100:101]
	s_mov_b32 m0, s21
	s_nop 0
	global_load_lds_dwordx4 v148, s[100:101]
	s_waitcnt vmcnt(8)
	s_waitcnt lgkmcnt(0)
	s_barrier
	s_setprio 1
	s_waitcnt lgkmcnt(0)
	v_mfma_f32_16x16x32_f16 v[76:79], v[48:51], v[194:197], v[76:79]
	v_mfma_f32_16x16x32_f16 v[72:75], v[64:67], v[194:197], v[72:75]
	v_mfma_f32_16x16x32_f16 v[60:63], v[48:51], v[202:205], v[60:63]
	v_mfma_f32_16x16x32_f16 v[56:59], v[64:67], v[202:205], v[56:59]
	v_mfma_f32_16x16x32_f16 v[28:31], v[48:51], v[210:213], v[28:31]
	v_mfma_f32_16x16x32_f16 v[24:27], v[64:67], v[210:213], v[24:27]
	v_mfma_f32_16x16x32_f16 v[12:15], v[48:51], v[218:221], v[12:15]
	v_mfma_f32_16x16x32_f16 v[8:11], v[64:67], v[218:221], v[8:11]
	v_mfma_f32_16x16x32_f16 v[76:79], v[52:55], v[198:201], v[76:79]
	v_mfma_f32_16x16x32_f16 v[72:75], v[68:71], v[198:201], v[72:75]
	v_mfma_f32_16x16x32_f16 v[60:63], v[52:55], v[206:209], v[60:63]
	v_mfma_f32_16x16x32_f16 v[56:59], v[68:71], v[206:209], v[56:59]
	v_mfma_f32_16x16x32_f16 v[28:31], v[52:55], v[214:217], v[28:31]
	v_mfma_f32_16x16x32_f16 v[24:27], v[68:71], v[214:217], v[24:27]
	v_mfma_f32_16x16x32_f16 v[12:15], v[52:55], v[222:225], v[12:15]
	v_mfma_f32_16x16x32_f16 v[8:11], v[68:71], v[222:225], v[8:11]
	v_mfma_f32_16x16x32_f16 v[32:35], v[156:159], v[194:197], v[32:35]
	v_mfma_f32_16x16x32_f16 v[68:71], v[168:171], v[198:201], v[32:35]
	v_mfma_f32_16x16x32_f16 v[32:35], v[186:189], v[194:197], v[36:39]
	v_mfma_f32_16x16x32_f16 v[64:67], v[190:193], v[198:201], v[32:35]
	v_mfma_f32_16x16x32_f16 v[32:35], v[156:159], v[202:205], v[40:43]
	v_mfma_f32_16x16x32_f16 v[52:55], v[168:171], v[206:209], v[32:35]
	v_mfma_f32_16x16x32_f16 v[32:35], v[186:189], v[202:205], v[44:47]
	v_mfma_f32_16x16x32_f16 v[20:23], v[156:159], v[210:213], v[20:23]
	v_mfma_f32_16x16x32_f16 v[16:19], v[186:189], v[210:213], v[16:19]
	v_mfma_f32_16x16x32_f16 v[4:7], v[156:159], v[218:221], v[4:7]
	v_mfma_f32_16x16x32_f16 v[0:3], v[186:189], v[218:221], v[0:3]
	v_mfma_f32_16x16x32_f16 v[48:51], v[190:193], v[206:209], v[32:35]
	v_mfma_f32_16x16x32_f16 v[20:23], v[168:171], v[214:217], v[20:23]
	v_mfma_f32_16x16x32_f16 v[16:19], v[190:193], v[214:217], v[16:19]
	v_mfma_f32_16x16x32_f16 v[4:7], v[168:171], v[222:225], v[4:7]
	v_mfma_f32_16x16x32_f16 v[0:3], v[190:193], v[222:225], v[0:3]
	s_setprio 0
	s_barrier
	s_add_i32 s61, s61, 2
	s_add_u32 s54, s54, 0x100
	s_addc_u32 s55, s55, 0
	s_add_u32 s49, s49, 0x100
	s_addc_u32 s60, s60, 0
	s_cmp_gt_u32 s61, 13
	s_cbranch_scc0 .LBB0_904
	s_and_b64 vcc, exec, s[44:45]
	s_cbranch_vccz .LBB0_907
	s_barrier
.LBB0_907:
	s_ashr_i32 s4, s34, 6
	s_mul_hi_i32 s5, s4, 0x5800
	s_mulk_i32 s4, 0x5800
	v_lshl_add_u32 v156, s34, 8, v162
	s_add_u32 s34, s14, s4
	s_addc_u32 s37, s15, s5
	s_lshl_b32 s4, s31, 8
	s_ashr_i32 s5, s4, 31
	s_lshl_b64 s[4:5], s[4:5], 2
	s_add_u32 s4, s34, s4
	s_addc_u32 s5, s37, s5
	s_add_u32 s4, s4, s30
	v_ashrrev_i32_e32 v157, 31, v156
	s_addc_u32 s5, s5, 0
	v_lshl_add_u64 v[158:159], v[156:157], 2, s[42:43]
	v_mov_b32_e32 v36, v242
	v_mov_b32_e32 v37, v243
	v_mov_b32_e32 v38, v244
	v_mov_b32_e32 v39, v245
	v_mov_b32_e32 v44, v246
	v_mov_b32_e32 v45, v247
	v_mov_b32_e32 v46, v248
	v_mov_b32_e32 v47, v249
	v_mov_b32_e32 v32, v174
	v_mov_b32_e32 v33, v175
	v_mov_b32_e32 v34, v176
	v_mov_b32_e32 v35, v177
	v_mov_b32_e32 v40, v238
	v_mov_b32_e32 v41, v239
	v_mov_b32_e32 v42, v240
	v_mov_b32_e32 v43, v241
	v_mov_b32_e32 v157, v147
	v_mov_b32_e32 v186, v149
	v_mov_b32_e32 v187, v151
	v_mov_b32_e32 v188, v153
	v_mov_b32_e32 v189, v155
	v_mov_b32_e32 v190, v167
	v_mov_b32_e32 v191, v173
	v_mov_b32_e32 v192, v250
	v_lshl_or_b32 v160, s31, 7, v164
	v_ashrrev_i32_e32 v161, 31, v160
	s_movk_i32 s12, 0x1600
	s_mov_b64 s[54:55], -1
	s_waitcnt vmcnt(8)
; __device__ __forceinline__ unsigned pk_bf16(float lo, float hi) { f32x2 v = {lo, hi}; bf16x2_t b = __builtin_convertvector(v, bf16x2_t); return __builtin_bit_cast(unsigned, b); }
;     __device__ __forceinline__ void operator()(const f32x4 (&acc)[2][2][4][2], const Unit& u, int wr, int wc, int fr, int fq) const {
;     ...
; #pragma unroll
;         for (int ai = 0; ai < 2; ++ai)
; #pragma unroll
;             for (int m = 0; m < 4; ++m) {
;                 float o[8]; const float rv = rsqrtf(rowss[row0 + ai * HALF + m * 16] * (1.0f / 1024.0f) + 1e-6f);
; #pragma unroll
;                 for (int n = 0; n < 2; ++n)
; #pragma unroll
;                     for (int j = 0; j < 4; ++j) { const float g = acc[ai][0][m][n][j] * rv + bz[0][n][j], up = acc[ai][1][m][n][j] * rv + bz[1][n][j];
;                         o[4 * n + j] = g * __builtin_amdgcn_rcpf(1.0f + __expf(-g)) * up; }
;                 u32x4 w; w.x = pk_bf16(o[0], o[1]); w.y = pk_bf16(o[2], o[3]); w.z = pk_bf16(o[4], o[5]); w.w = pk_bf16(o[6], o[7]);
;                 *(u32x4*)(act + (size_t)(row0 + ai * HALF + m * 16) * 2816 + col0) = w;
;             }
	v_fmamk_f32 v157, v157, 0x3a800000, v227
	s_nop 0
	v_rsq_f32_e32 v157, v157
	s_nop 0
	v_mov_b32_e32 v168, v157
	v_pk_fma_f32 v[142:143], v[142:143], v[168:169], v[44:45] op_sel_hi:[1,0,1]
	v_pk_fma_f32 v[134:135], v[134:135], v[168:169], v[40:41] op_sel_hi:[1,0,1]
	v_mul_f32_e32 v157, 0xbfb8aa3b, v142
	v_exp_f32_e32 v157, v157
	v_pk_fma_f32 v[136:137], v[136:137], v[168:169], v[42:43] op_sel_hi:[1,0,1]
	v_pk_fma_f32 v[138:139], v[138:139], v[168:169], v[36:37] op_sel_hi:[1,0,1]
	v_pk_fma_f32 v[130:131], v[130:131], v[168:169], v[32:33] op_sel_hi:[1,0,1]
	v_add_f32_e32 v157, 1.0, v157
	v_rcp_f32_e32 v170, v157
	v_mul_f32_e32 v157, 0xbfb8aa3b, v143
	v_exp_f32_e32 v157, v157
	v_pk_fma_f32 v[132:133], v[132:133], v[168:169], v[34:35] op_sel_hi:[1,0,1]
	v_add_f32_e32 v157, 1.0, v157
	v_rcp_f32_e32 v171, v157
	s_nop 0
	v_pk_mul_f32 v[142:143], v[142:143], v[170:171]
	s_nop 0
	v_pk_mul_f32 v[134:135], v[134:135], v[142:143]
	v_pk_fma_f32 v[142:143], v[144:145], v[168:169], v[46:47] op_sel_hi:[1,0,1]
	s_nop 0
	v_mul_f32_e32 v144, 0xbfb8aa3b, v142
	v_mul_f32_e32 v145, 0xbfb8aa3b, v143
	v_exp_f32_e32 v144, v144
	v_exp_f32_e32 v145, v145
	v_add_f32_e32 v144, 1.0, v144
	v_add_f32_e32 v145, 1.0, v145
	v_rcp_f32_e32 v144, v144
	v_rcp_f32_e32 v145, v145
	s_nop 0
	v_pk_mul_f32 v[142:143], v[142:143], v[144:145]
	s_nop 0
	v_pk_mul_f32 v[136:137], v[136:137], v[142:143]
	v_mul_f32_e32 v142, 0xbfb8aa3b, v138
	v_mul_f32_e32 v143, 0xbfb8aa3b, v139
	v_exp_f32_e32 v142, v142
	v_exp_f32_e32 v143, v143
	v_add_f32_e32 v142, 1.0, v142
	v_add_f32_e32 v143, 1.0, v143
	v_rcp_f32_e32 v142, v142
	v_rcp_f32_e32 v143, v143
	s_nop 0
	v_pk_mul_f32 v[138:139], v[138:139], v[142:143]
	s_nop 0
	v_pk_mul_f32 v[138:139], v[130:131], v[138:139]
	v_pk_fma_f32 v[130:131], v[140:141], v[168:169], v[38:39] op_sel_hi:[1,0,1]
	s_nop 0
	v_mul_f32_e32 v140, 0xbfb8aa3b, v130
	v_mul_f32_e32 v141, 0xbfb8aa3b, v131
	v_exp_f32_e32 v140, v140
	v_exp_f32_e32 v141, v141
	v_add_f32_e32 v140, 1.0, v140
	v_add_f32_e32 v141, 1.0, v141
	v_rcp_f32_e32 v140, v140
	v_rcp_f32_e32 v141, v141
	s_nop 0
	v_pk_mul_f32 v[130:131], v[130:131], v[140:141]
	s_nop 0
	v_pk_mul_f32 v[140:141], v[132:133], v[130:131]
	v_cvt_pk_bf16_f32 v130, v134, v135
	v_mov_b64_e32 v[134:135], s[2:3]
	v_cvt_pk_bf16_f32 v131, v136, v137
	v_cvt_pk_bf16_f32 v132, v138, v139
	v_mad_i64_i32 v[138:139], s[4:5], v156, s12, v[134:135]
	v_lshlrev_b64 v[136:137], 1, v[160:161]
	v_cvt_pk_bf16_f32 v133, v140, v141
	v_lshl_add_u64 v[138:139], v[138:139], 0, v[136:137]
	global_store_dwordx4 v[138:139], v[130:133], off
	s_nop 1
	v_or_b32_e32 v130, 16, v156
	v_fmamk_f32 v131, v186, 0x3a800000, v227
	s_nop 0
	v_rsq_f32_e32 v131, v131
	s_nop 0
	v_mov_b32_e32 v132, v131
	v_pk_fma_f32 v[124:125], v[124:125], v[132:133], v[44:45] op_sel_hi:[1,0,1]
	v_pk_fma_f32 v[116:117], v[116:117], v[132:133], v[40:41] op_sel_hi:[1,0,1]
	v_mul_f32_e32 v131, 0xbfb8aa3b, v124
	v_exp_f32_e32 v131, v131
	v_pk_fma_f32 v[118:119], v[118:119], v[132:133], v[42:43] op_sel_hi:[1,0,1]
	v_pk_fma_f32 v[120:121], v[120:121], v[132:133], v[36:37] op_sel_hi:[1,0,1]
	v_pk_fma_f32 v[112:113], v[112:113], v[132:133], v[32:33] op_sel_hi:[1,0,1]
	v_add_f32_e32 v131, 1.0, v131
	v_rcp_f32_e32 v138, v131
	v_mul_f32_e32 v131, 0xbfb8aa3b, v125
	v_exp_f32_e32 v131, v131
	v_pk_fma_f32 v[114:115], v[114:115], v[132:133], v[34:35] op_sel_hi:[1,0,1]
	v_add_f32_e32 v131, 1.0, v131
	v_rcp_f32_e32 v139, v131
	s_nop 0
	v_pk_mul_f32 v[124:125], v[124:125], v[138:139]
	s_nop 0
	v_pk_mul_f32 v[116:117], v[116:117], v[124:125]
	v_pk_fma_f32 v[124:125], v[126:127], v[132:133], v[46:47] op_sel_hi:[1,0,1]
	s_nop 0
	v_mul_f32_e32 v126, 0xbfb8aa3b, v124
	v_mul_f32_e32 v127, 0xbfb8aa3b, v125
	v_exp_f32_e32 v126, v126
	v_exp_f32_e32 v127, v127
	v_add_f32_e32 v126, 1.0, v126
	v_add_f32_e32 v127, 1.0, v127
	v_rcp_f32_e32 v126, v126
	v_rcp_f32_e32 v127, v127
	s_nop 0
	v_pk_mul_f32 v[124:125], v[124:125], v[126:127]
	s_nop 0
	v_pk_mul_f32 v[118:119], v[118:119], v[124:125]
	v_mul_f32_e32 v124, 0xbfb8aa3b, v120
	v_mul_f32_e32 v125, 0xbfb8aa3b, v121
	v_exp_f32_e32 v124, v124
	v_exp_f32_e32 v125, v125
	v_add_f32_e32 v124, 1.0, v124
	v_add_f32_e32 v125, 1.0, v125
	v_rcp_f32_e32 v124, v124
	v_rcp_f32_e32 v125, v125
	s_nop 0
	v_pk_mul_f32 v[120:121], v[120:121], v[124:125]
	s_nop 0
	v_pk_mul_f32 v[120:121], v[112:113], v[120:121]
	v_pk_fma_f32 v[112:113], v[122:123], v[132:133], v[38:39] op_sel_hi:[1,0,1]
	s_nop 0
	v_mul_f32_e32 v122, 0xbfb8aa3b, v112
	v_mul_f32_e32 v123, 0xbfb8aa3b, v113
	v_exp_f32_e32 v122, v122
	v_exp_f32_e32 v123, v123
	v_add_f32_e32 v122, 1.0, v122
	v_add_f32_e32 v123, 1.0, v123
	v_rcp_f32_e32 v122, v122
	v_rcp_f32_e32 v123, v123
	s_nop 0
	v_pk_mul_f32 v[112:113], v[112:113], v[122:123]
	s_nop 0
	v_pk_mul_f32 v[122:123], v[114:115], v[112:113]
	v_cvt_pk_bf16_f32 v112, v116, v117
	v_mad_i64_i32 v[116:117], s[4:5], v130, s12, v[134:135]
	v_cvt_pk_bf16_f32 v113, v118, v119
	v_cvt_pk_bf16_f32 v114, v120, v121
	v_cvt_pk_bf16_f32 v115, v122, v123
	v_lshl_add_u64 v[116:117], v[116:117], 0, v[136:137]
	global_store_dwordx4 v[116:117], v[112:115], off
	s_nop 1
	v_or_b32_e32 v112, 32, v156
	v_fmamk_f32 v113, v187, 0x3a800000, v227
	s_nop 0
	v_rsq_f32_e32 v113, v113
	s_nop 0
	v_mov_b32_e32 v114, v113
	v_pk_fma_f32 v[108:109], v[108:109], v[114:115], v[44:45] op_sel_hi:[1,0,1]
	v_pk_fma_f32 v[100:101], v[100:101], v[114:115], v[40:41] op_sel_hi:[1,0,1]
	v_mul_f32_e32 v113, 0xbfb8aa3b, v108
	v_exp_f32_e32 v113, v113
	v_pk_fma_f32 v[102:103], v[102:103], v[114:115], v[42:43] op_sel_hi:[1,0,1]
	v_pk_fma_f32 v[104:105], v[104:105], v[114:115], v[36:37] op_sel_hi:[1,0,1]
	v_pk_fma_f32 v[96:97], v[96:97], v[114:115], v[32:33] op_sel_hi:[1,0,1]
; __device__ __forceinline__ unsigned pk_bf16(float lo, float hi) { f32x2 v = {lo, hi}; bf16x2_t b = __builtin_convertvector(v, bf16x2_t); return __builtin_bit_cast(unsigned, b); }
;     __device__ __forceinline__ void operator()(const f32x4 (&acc)[2][2][4][2], const Unit& u, int wr, int wc, int fr, int fq) const {
;     ...
; #pragma unroll
;         for (int ai = 0; ai < 2; ++ai)
; #pragma unroll
;             for (int m = 0; m < 4; ++m) {
;                 float o[8]; const float rv = rsqrtf(rowss[row0 + ai * HALF + m * 16] * (1.0f / 1024.0f) + 1e-6f);
; #pragma unroll
;                 for (int n = 0; n < 2; ++n)
; #pragma unroll
;                     for (int j = 0; j < 4; ++j) { const float g = acc[ai][0][m][n][j] * rv + bz[0][n][j], up = acc[ai][1][m][n][j] * rv + bz[1][n][j];
;                         o[4 * n + j] = g * __builtin_amdgcn_rcpf(1.0f + __expf(-g)) * up; }
;                 u32x4 w; w.x = pk_bf16(o[0], o[1]); w.y = pk_bf16(o[2], o[3]); w.z = pk_bf16(o[4], o[5]); w.w = pk_bf16(o[6], o[7]);
;                 *(u32x4*)(act + (size_t)(row0 + ai * HALF + m * 16) * 2816 + col0) = w;
;             }
	v_add_f32_e32 v113, 1.0, v113
	v_rcp_f32_e32 v116, v113
	v_mul_f32_e32 v113, 0xbfb8aa3b, v109
	v_exp_f32_e32 v113, v113
	v_pk_fma_f32 v[98:99], v[98:99], v[114:115], v[34:35] op_sel_hi:[1,0,1]
	v_add_f32_e32 v113, 1.0, v113
	v_rcp_f32_e32 v117, v113
	s_nop 0
	v_pk_mul_f32 v[108:109], v[108:109], v[116:117]
	s_nop 0
	v_pk_mul_f32 v[100:101], v[100:101], v[108:109]
	v_pk_fma_f32 v[108:109], v[110:111], v[114:115], v[46:47] op_sel_hi:[1,0,1]
	s_nop 0
	v_mul_f32_e32 v110, 0xbfb8aa3b, v108
	v_mul_f32_e32 v111, 0xbfb8aa3b, v109
	v_exp_f32_e32 v110, v110
	v_exp_f32_e32 v111, v111
	v_add_f32_e32 v110, 1.0, v110
	v_add_f32_e32 v111, 1.0, v111
	v_rcp_f32_e32 v110, v110
	v_rcp_f32_e32 v111, v111
	s_nop 0
	v_pk_mul_f32 v[108:109], v[108:109], v[110:111]
	s_nop 0
	v_pk_mul_f32 v[102:103], v[102:103], v[108:109]
	v_mul_f32_e32 v108, 0xbfb8aa3b, v104
	v_mul_f32_e32 v109, 0xbfb8aa3b, v105
	v_exp_f32_e32 v108, v108
	v_exp_f32_e32 v109, v109
	v_add_f32_e32 v108, 1.0, v108
	v_add_f32_e32 v109, 1.0, v109
	v_rcp_f32_e32 v108, v108
	v_rcp_f32_e32 v109, v109
	s_nop 0
	v_pk_mul_f32 v[104:105], v[104:105], v[108:109]
	s_nop 0
	v_pk_mul_f32 v[104:105], v[96:97], v[104:105]
	v_pk_fma_f32 v[96:97], v[106:107], v[114:115], v[38:39] op_sel_hi:[1,0,1]
	s_nop 0
	v_mul_f32_e32 v106, 0xbfb8aa3b, v96
	v_mul_f32_e32 v107, 0xbfb8aa3b, v97
	v_exp_f32_e32 v106, v106
	v_exp_f32_e32 v107, v107
	v_add_f32_e32 v106, 1.0, v106
	v_add_f32_e32 v107, 1.0, v107
	v_rcp_f32_e32 v106, v106
	v_rcp_f32_e32 v107, v107
	s_nop 0
	v_pk_mul_f32 v[96:97], v[96:97], v[106:107]
	s_nop 0
	v_pk_mul_f32 v[106:107], v[98:99], v[96:97]
	v_cvt_pk_bf16_f32 v96, v100, v101
	v_mad_i64_i32 v[100:101], s[4:5], v112, s12, v[134:135]
	v_cvt_pk_bf16_f32 v97, v102, v103
	v_cvt_pk_bf16_f32 v98, v104, v105
	v_cvt_pk_bf16_f32 v99, v106, v107
	v_lshl_add_u64 v[100:101], v[100:101], 0, v[136:137]
	global_store_dwordx4 v[100:101], v[96:99], off
	s_nop 1
	v_or_b32_e32 v96, 48, v156
	v_fmamk_f32 v97, v188, 0x3a800000, v227
	s_nop 0
	v_rsq_f32_e32 v97, v97
	s_nop 0
	v_mov_b32_e32 v98, v97
	v_pk_fma_f32 v[92:93], v[92:93], v[98:99], v[44:45] op_sel_hi:[1,0,1]
	v_pk_fma_f32 v[84:85], v[84:85], v[98:99], v[40:41] op_sel_hi:[1,0,1]
	v_mul_f32_e32 v97, 0xbfb8aa3b, v92
	v_exp_f32_e32 v97, v97
	v_pk_fma_f32 v[86:87], v[86:87], v[98:99], v[42:43] op_sel_hi:[1,0,1]
	v_pk_fma_f32 v[88:89], v[88:89], v[98:99], v[36:37] op_sel_hi:[1,0,1]
	v_pk_fma_f32 v[80:81], v[80:81], v[98:99], v[32:33] op_sel_hi:[1,0,1]
	v_add_f32_e32 v97, 1.0, v97
	v_rcp_f32_e32 v100, v97
	v_mul_f32_e32 v97, 0xbfb8aa3b, v93
	v_exp_f32_e32 v97, v97
	v_pk_fma_f32 v[82:83], v[82:83], v[98:99], v[34:35] op_sel_hi:[1,0,1]
	v_add_f32_e32 v97, 1.0, v97
	v_rcp_f32_e32 v101, v97
	s_nop 0
	v_pk_mul_f32 v[92:93], v[92:93], v[100:101]
	s_nop 0
	v_pk_mul_f32 v[84:85], v[84:85], v[92:93]
	v_pk_fma_f32 v[92:93], v[94:95], v[98:99], v[46:47] op_sel_hi:[1,0,1]
	s_nop 0
	v_mul_f32_e32 v94, 0xbfb8aa3b, v92
	v_mul_f32_e32 v95, 0xbfb8aa3b, v93
	v_exp_f32_e32 v94, v94
	v_exp_f32_e32 v95, v95
	v_add_f32_e32 v94, 1.0, v94
	v_add_f32_e32 v95, 1.0, v95
	v_rcp_f32_e32 v94, v94
	v_rcp_f32_e32 v95, v95
	s_nop 0
	v_pk_mul_f32 v[92:93], v[92:93], v[94:95]
	s_nop 0
	v_pk_mul_f32 v[86:87], v[86:87], v[92:93]
	v_mul_f32_e32 v92, 0xbfb8aa3b, v88
	v_mul_f32_e32 v93, 0xbfb8aa3b, v89
	v_exp_f32_e32 v92, v92
	v_exp_f32_e32 v93, v93
	v_add_f32_e32 v92, 1.0, v92
	v_add_f32_e32 v93, 1.0, v93
	v_rcp_f32_e32 v92, v92
	v_rcp_f32_e32 v93, v93
	s_nop 0
	v_pk_mul_f32 v[88:89], v[88:89], v[92:93]
	s_nop 0
	v_pk_mul_f32 v[88:89], v[80:81], v[88:89]
	v_pk_fma_f32 v[80:81], v[90:91], v[98:99], v[38:39] op_sel_hi:[1,0,1]
	s_nop 0
	v_mul_f32_e32 v90, 0xbfb8aa3b, v80
	v_mul_f32_e32 v91, 0xbfb8aa3b, v81
	v_exp_f32_e32 v90, v90
	v_exp_f32_e32 v91, v91
	v_add_f32_e32 v90, 1.0, v90
	v_add_f32_e32 v91, 1.0, v91
	v_rcp_f32_e32 v90, v90
	v_rcp_f32_e32 v91, v91
	s_nop 0
	v_pk_mul_f32 v[80:81], v[80:81], v[90:91]
	s_nop 0
	v_pk_mul_f32 v[90:91], v[82:83], v[80:81]
	v_cvt_pk_bf16_f32 v80, v84, v85
	v_mad_i64_i32 v[84:85], s[4:5], v96, s12, v[134:135]
	v_cvt_pk_bf16_f32 v81, v86, v87
	v_cvt_pk_bf16_f32 v82, v88, v89
	v_cvt_pk_bf16_f32 v83, v90, v91
	v_lshl_add_u64 v[84:85], v[84:85], 0, v[136:137]
	global_store_dwordx4 v[84:85], v[80:83], off
	s_nop 0
	s_nop 0
	v_add_u32_e32 v81, 0x80, v156
	v_fmamk_f32 v80, v189, 0x3a800000, v227
	s_nop 0
	v_rsq_f32_e32 v80, v80
	s_nop 0
	v_pk_fma_f32 v[76:77], v[76:77], v[80:81], v[44:45] op_sel_hi:[1,0,1]
	v_pk_fma_f32 v[68:69], v[68:69], v[80:81], v[40:41] op_sel_hi:[1,0,1]
	v_mul_f32_e32 v82, 0xbfb8aa3b, v76
	v_mul_f32_e32 v83, 0xbfb8aa3b, v77
	v_exp_f32_e32 v82, v82
	v_exp_f32_e32 v83, v83
	v_pk_fma_f32 v[70:71], v[70:71], v[80:81], v[42:43] op_sel_hi:[1,0,1]
	v_pk_fma_f32 v[72:73], v[72:73], v[80:81], v[36:37] op_sel_hi:[1,0,1]
	v_add_f32_e32 v82, 1.0, v82
	v_add_f32_e32 v83, 1.0, v83
	v_rcp_f32_e32 v82, v82
	v_rcp_f32_e32 v83, v83
	v_pk_fma_f32 v[64:65], v[64:65], v[80:81], v[32:33] op_sel_hi:[1,0,1]
	v_pk_fma_f32 v[66:67], v[66:67], v[80:81], v[34:35] op_sel_hi:[1,0,1]
	v_pk_mul_f32 v[76:77], v[76:77], v[82:83]
	s_nop 0
	v_pk_mul_f32 v[68:69], v[68:69], v[76:77]
	v_pk_fma_f32 v[76:77], v[78:79], v[80:81], v[46:47] op_sel_hi:[1,0,1]
	s_nop 0
	v_mul_f32_e32 v78, 0xbfb8aa3b, v76
	v_mul_f32_e32 v79, 0xbfb8aa3b, v77
	v_exp_f32_e32 v78, v78
	v_exp_f32_e32 v79, v79
	v_add_f32_e32 v78, 1.0, v78
	v_add_f32_e32 v79, 1.0, v79
	v_rcp_f32_e32 v78, v78
	v_rcp_f32_e32 v79, v79
	s_nop 0
	v_pk_mul_f32 v[76:77], v[76:77], v[78:79]
	s_nop 0
	v_pk_mul_f32 v[70:71], v[70:71], v[76:77]
	v_mul_f32_e32 v76, 0xbfb8aa3b, v72
	v_mul_f32_e32 v77, 0xbfb8aa3b, v73
	v_exp_f32_e32 v76, v76
	v_exp_f32_e32 v77, v77
; __device__ __forceinline__ unsigned pk_bf16(float lo, float hi) { f32x2 v = {lo, hi}; bf16x2_t b = __builtin_convertvector(v, bf16x2_t); return __builtin_bit_cast(unsigned, b); }
;     __device__ __forceinline__ void operator()(const f32x4 (&acc)[2][2][4][2], const Unit& u, int wr, int wc, int fr, int fq) const {
;     ...
; #pragma unroll
;         for (int ai = 0; ai < 2; ++ai)
; #pragma unroll
;             for (int m = 0; m < 4; ++m) {
;                 float o[8]; const float rv = rsqrtf(rowss[row0 + ai * HALF + m * 16] * (1.0f / 1024.0f) + 1e-6f);
; #pragma unroll
;                 for (int n = 0; n < 2; ++n)
; #pragma unroll
;                     for (int j = 0; j < 4; ++j) { const float g = acc[ai][0][m][n][j] * rv + bz[0][n][j], up = acc[ai][1][m][n][j] * rv + bz[1][n][j];
;                         o[4 * n + j] = g * __builtin_amdgcn_rcpf(1.0f + __expf(-g)) * up; }
;                 u32x4 w; w.x = pk_bf16(o[0], o[1]); w.y = pk_bf16(o[2], o[3]); w.z = pk_bf16(o[4], o[5]); w.w = pk_bf16(o[6], o[7]);
;                 *(u32x4*)(act + (size_t)(row0 + ai * HALF + m * 16) * 2816 + col0) = w;
;             }
	v_add_f32_e32 v76, 1.0, v76
	v_add_f32_e32 v77, 1.0, v77
	v_rcp_f32_e32 v76, v76
	v_rcp_f32_e32 v77, v77
	s_nop 0
	v_pk_mul_f32 v[72:73], v[72:73], v[76:77]
	s_nop 0
	v_pk_mul_f32 v[72:73], v[64:65], v[72:73]
	v_pk_fma_f32 v[64:65], v[74:75], v[80:81], v[38:39] op_sel_hi:[1,0,1]
	s_nop 0
	v_mul_f32_e32 v74, 0xbfb8aa3b, v64
	v_mul_f32_e32 v75, 0xbfb8aa3b, v65
	v_exp_f32_e32 v74, v74
	v_exp_f32_e32 v75, v75
	v_add_f32_e32 v74, 1.0, v74
	v_add_f32_e32 v75, 1.0, v75
	v_rcp_f32_e32 v74, v74
	v_rcp_f32_e32 v75, v75
	s_nop 0
	v_pk_mul_f32 v[64:65], v[64:65], v[74:75]
	s_nop 0
	v_pk_mul_f32 v[74:75], v[66:67], v[64:65]
	v_cvt_pk_bf16_f32 v64, v68, v69
	v_mad_i64_i32 v[68:69], s[4:5], v81, s12, v[134:135]
	v_cvt_pk_bf16_f32 v65, v70, v71
	v_cvt_pk_bf16_f32 v66, v72, v73
	v_cvt_pk_bf16_f32 v67, v74, v75
	v_lshl_add_u64 v[68:69], v[68:69], 0, v[136:137]
	global_store_dwordx4 v[68:69], v[64:67], off
	s_nop 0
	s_nop 0
	v_add_u32_e32 v65, 0x90, v156
	v_fmamk_f32 v64, v190, 0x3a800000, v227
	s_nop 0
	v_rsq_f32_e32 v64, v64
	s_nop 0
	v_pk_fma_f32 v[60:61], v[60:61], v[64:65], v[44:45] op_sel_hi:[1,0,1]
	v_pk_fma_f32 v[52:53], v[52:53], v[64:65], v[40:41] op_sel_hi:[1,0,1]
	v_mul_f32_e32 v66, 0xbfb8aa3b, v60
	v_mul_f32_e32 v67, 0xbfb8aa3b, v61
	v_exp_f32_e32 v66, v66
	v_exp_f32_e32 v67, v67
	v_pk_fma_f32 v[54:55], v[54:55], v[64:65], v[42:43] op_sel_hi:[1,0,1]
	v_pk_fma_f32 v[56:57], v[56:57], v[64:65], v[36:37] op_sel_hi:[1,0,1]
	v_add_f32_e32 v66, 1.0, v66
	v_add_f32_e32 v67, 1.0, v67
	v_rcp_f32_e32 v66, v66
	v_rcp_f32_e32 v67, v67
	v_pk_fma_f32 v[48:49], v[48:49], v[64:65], v[32:33] op_sel_hi:[1,0,1]
	v_pk_fma_f32 v[50:51], v[50:51], v[64:65], v[34:35] op_sel_hi:[1,0,1]
	v_pk_mul_f32 v[60:61], v[60:61], v[66:67]
	s_nop 0
	v_pk_mul_f32 v[52:53], v[52:53], v[60:61]
	v_pk_fma_f32 v[60:61], v[62:63], v[64:65], v[46:47] op_sel_hi:[1,0,1]
	s_nop 0
	v_mul_f32_e32 v62, 0xbfb8aa3b, v60
	v_mul_f32_e32 v63, 0xbfb8aa3b, v61
	v_exp_f32_e32 v62, v62
	v_exp_f32_e32 v63, v63
	v_add_f32_e32 v62, 1.0, v62
	v_add_f32_e32 v63, 1.0, v63
	v_rcp_f32_e32 v62, v62
	v_rcp_f32_e32 v63, v63
	s_nop 0
	v_pk_mul_f32 v[60:61], v[60:61], v[62:63]
	s_nop 0
	v_pk_mul_f32 v[54:55], v[54:55], v[60:61]
	v_mul_f32_e32 v60, 0xbfb8aa3b, v56
	v_mul_f32_e32 v61, 0xbfb8aa3b, v57
	v_exp_f32_e32 v60, v60
	v_exp_f32_e32 v61, v61
	v_add_f32_e32 v60, 1.0, v60
	v_add_f32_e32 v61, 1.0, v61
	v_rcp_f32_e32 v60, v60
	v_rcp_f32_e32 v61, v61
	s_nop 0
	v_pk_mul_f32 v[56:57], v[56:57], v[60:61]
	s_nop 0
	v_pk_mul_f32 v[56:57], v[48:49], v[56:57]
	v_pk_fma_f32 v[48:49], v[58:59], v[64:65], v[38:39] op_sel_hi:[1,0,1]
	s_nop 0
	v_mul_f32_e32 v58, 0xbfb8aa3b, v48
	v_mul_f32_e32 v59, 0xbfb8aa3b, v49
	v_exp_f32_e32 v58, v58
	v_exp_f32_e32 v59, v59
	v_add_f32_e32 v58, 1.0, v58
	v_add_f32_e32 v59, 1.0, v59
	v_rcp_f32_e32 v58, v58
	v_rcp_f32_e32 v59, v59
	s_nop 0
	v_pk_mul_f32 v[48:49], v[48:49], v[58:59]
	s_nop 0
	v_pk_mul_f32 v[58:59], v[50:51], v[48:49]
	v_cvt_pk_bf16_f32 v48, v52, v53
	v_mad_i64_i32 v[52:53], s[4:5], v65, s12, v[134:135]
	v_cvt_pk_bf16_f32 v49, v54, v55
	v_cvt_pk_bf16_f32 v50, v56, v57
	v_cvt_pk_bf16_f32 v51, v58, v59
	v_lshl_add_u64 v[52:53], v[52:53], 0, v[136:137]
	global_store_dwordx4 v[52:53], v[48:51], off
	s_nop 0
	s_nop 0
	v_add_u32_e32 v49, 0xa0, v156
	v_fmamk_f32 v48, v191, 0x3a800000, v227
	s_nop 0
	v_rsq_f32_e32 v48, v48
	s_nop 0
	v_pk_fma_f32 v[28:29], v[28:29], v[48:49], v[44:45] op_sel_hi:[1,0,1]
	v_pk_fma_f32 v[20:21], v[20:21], v[48:49], v[40:41] op_sel_hi:[1,0,1]
	v_mul_f32_e32 v50, 0xbfb8aa3b, v28
	v_mul_f32_e32 v51, 0xbfb8aa3b, v29
	v_exp_f32_e32 v50, v50
	v_exp_f32_e32 v51, v51
	v_pk_fma_f32 v[22:23], v[22:23], v[48:49], v[42:43] op_sel_hi:[1,0,1]
	v_pk_fma_f32 v[24:25], v[24:25], v[48:49], v[36:37] op_sel_hi:[1,0,1]
	v_add_f32_e32 v50, 1.0, v50
	v_add_f32_e32 v51, 1.0, v51
	v_rcp_f32_e32 v50, v50
	v_rcp_f32_e32 v51, v51
	v_pk_fma_f32 v[16:17], v[16:17], v[48:49], v[32:33] op_sel_hi:[1,0,1]
; __device__ __forceinline__ unsigned pk_bf16(float lo, float hi) { f32x2 v = {lo, hi}; bf16x2_t b = __builtin_convertvector(v, bf16x2_t); return __builtin_bit_cast(unsigned, b); }
; #define PG8_BAR __builtin_amdgcn_s_barrier()
;     __device__ __forceinline__ void operator()(const f32x4 (&acc)[2][2][4][2], const Unit& u, int wr, int wc, int fr, int fq) const {
;     ...
; #pragma unroll
;         for (int ai = 0; ai < 2; ++ai)
; #pragma unroll
;             for (int m = 0; m < 4; ++m) {
;                 float o[8]; const float rv = rsqrtf(rowss[row0 + ai * HALF + m * 16] * (1.0f / 1024.0f) + 1e-6f);
; #pragma unroll
;                 for (int n = 0; n < 2; ++n)
; #pragma unroll
;                     for (int j = 0; j < 4; ++j) { const float g = acc[ai][0][m][n][j] * rv + bz[0][n][j], up = acc[ai][1][m][n][j] * rv + bz[1][n][j];
;                         o[4 * n + j] = g * __builtin_amdgcn_rcpf(1.0f + __expf(-g)) * up; }
;                 u32x4 w; w.x = pk_bf16(o[0], o[1]); w.y = pk_bf16(o[2], o[3]); w.z = pk_bf16(o[4], o[5]); w.w = pk_bf16(o[6], o[7]);
;                 *(u32x4*)(act + (size_t)(row0 + ai * HALF + m * 16) * 2816 + col0) = w;
;             }
; template <class Epi, class Sched, bool ALIGN_EPI = false, bool SP2 = false, bool F16 = false>
; __device__ __forceinline__ void gemm_phase(PG8_LAS unsigned char* lds, const Gemm g, const Sched& S, const Epi& E) {
;     ...
;         if (!has_next) break;
; #pragma unroll
;         for (int a = 0; a < 2; ++a)
; #pragma unroll
;             for (int b = 0; b < 2; ++b)
; #pragma unroll
;                 for (int m = 0; m < 4; ++m)
; #pragma unroll
;                     for (int n = 0; n < 2; ++n) acc[a][b][m][n] = (f32x4){0.f, 0.f, 0.f, 0.f};
;         cur = nxt; cA = nA; cB = nB; ++ui;
;         if constexpr (ALIGN_EPI) { if (wr == 1) PG8_BAR; }
;     }
	v_pk_fma_f32 v[18:19], v[18:19], v[48:49], v[34:35] op_sel_hi:[1,0,1]
	v_pk_mul_f32 v[28:29], v[28:29], v[50:51]
	s_nop 0
	v_pk_mul_f32 v[20:21], v[20:21], v[28:29]
	v_pk_fma_f32 v[28:29], v[30:31], v[48:49], v[46:47] op_sel_hi:[1,0,1]
	s_nop 0
	v_mul_f32_e32 v30, 0xbfb8aa3b, v28
	v_mul_f32_e32 v31, 0xbfb8aa3b, v29
	v_exp_f32_e32 v30, v30
	v_exp_f32_e32 v31, v31
	v_add_f32_e32 v30, 1.0, v30
	v_add_f32_e32 v31, 1.0, v31
	v_rcp_f32_e32 v30, v30
	v_rcp_f32_e32 v31, v31
	s_nop 0
	v_pk_mul_f32 v[28:29], v[28:29], v[30:31]
	s_nop 0
	v_pk_mul_f32 v[22:23], v[22:23], v[28:29]
	v_mul_f32_e32 v28, 0xbfb8aa3b, v24
	v_mul_f32_e32 v29, 0xbfb8aa3b, v25
	v_exp_f32_e32 v28, v28
	v_exp_f32_e32 v29, v29
	v_add_f32_e32 v28, 1.0, v28
	v_add_f32_e32 v29, 1.0, v29
	v_rcp_f32_e32 v28, v28
	v_rcp_f32_e32 v29, v29
	s_nop 0
	v_pk_mul_f32 v[24:25], v[24:25], v[28:29]
	s_nop 0
	v_pk_mul_f32 v[24:25], v[16:17], v[24:25]
	v_pk_fma_f32 v[16:17], v[26:27], v[48:49], v[38:39] op_sel_hi:[1,0,1]
	s_nop 0
	v_mul_f32_e32 v26, 0xbfb8aa3b, v16
	v_mul_f32_e32 v27, 0xbfb8aa3b, v17
	v_exp_f32_e32 v26, v26
	v_exp_f32_e32 v27, v27
	v_add_f32_e32 v26, 1.0, v26
	v_add_f32_e32 v27, 1.0, v27
	v_rcp_f32_e32 v26, v26
	v_rcp_f32_e32 v27, v27
	s_nop 0
	v_pk_mul_f32 v[16:17], v[16:17], v[26:27]
	s_nop 0
	v_pk_mul_f32 v[26:27], v[18:19], v[16:17]
	v_cvt_pk_bf16_f32 v16, v20, v21
	v_mad_i64_i32 v[20:21], s[4:5], v49, s12, v[134:135]
	v_cvt_pk_bf16_f32 v17, v22, v23
	v_cvt_pk_bf16_f32 v18, v24, v25
	v_cvt_pk_bf16_f32 v19, v26, v27
	v_lshl_add_u64 v[20:21], v[20:21], 0, v[136:137]
	global_store_dwordx4 v[20:21], v[16:19], off
	s_nop 0
	s_nop 0
	v_add_u32_e32 v17, 0xb0, v156
	v_fmamk_f32 v16, v192, 0x3a800000, v227
	s_nop 0
	v_rsq_f32_e32 v16, v16
	s_nop 0
	v_pk_fma_f32 v[12:13], v[12:13], v[16:17], v[44:45] op_sel_hi:[1,0,1]
	v_pk_fma_f32 v[4:5], v[4:5], v[16:17], v[40:41] op_sel_hi:[1,0,1]
	v_mul_f32_e32 v18, 0xbfb8aa3b, v12
	v_mul_f32_e32 v19, 0xbfb8aa3b, v13
	v_exp_f32_e32 v18, v18
	v_exp_f32_e32 v19, v19
	v_pk_fma_f32 v[6:7], v[6:7], v[16:17], v[42:43] op_sel_hi:[1,0,1]
	v_pk_fma_f32 v[8:9], v[8:9], v[16:17], v[36:37] op_sel_hi:[1,0,1]
	v_add_f32_e32 v18, 1.0, v18
	v_add_f32_e32 v19, 1.0, v19
	v_rcp_f32_e32 v18, v18
	v_rcp_f32_e32 v19, v19
	v_pk_fma_f32 v[0:1], v[0:1], v[16:17], v[32:33] op_sel_hi:[1,0,1]
	v_pk_fma_f32 v[2:3], v[2:3], v[16:17], v[34:35] op_sel_hi:[1,0,1]
	s_andn2_b64 vcc, exec, s[40:41]
	v_pk_mul_f32 v[12:13], v[12:13], v[18:19]
	s_nop 0
	v_pk_mul_f32 v[4:5], v[4:5], v[12:13]
	v_pk_fma_f32 v[12:13], v[14:15], v[16:17], v[46:47] op_sel_hi:[1,0,1]
	s_nop 0
	v_mul_f32_e32 v14, 0xbfb8aa3b, v12
	v_mul_f32_e32 v15, 0xbfb8aa3b, v13
	v_exp_f32_e32 v14, v14
	v_exp_f32_e32 v15, v15
	v_add_f32_e32 v14, 1.0, v14
	v_add_f32_e32 v15, 1.0, v15
	v_rcp_f32_e32 v14, v14
	v_rcp_f32_e32 v15, v15
	s_nop 0
	v_pk_mul_f32 v[12:13], v[12:13], v[14:15]
	s_nop 0
	v_pk_mul_f32 v[6:7], v[6:7], v[12:13]
	v_mul_f32_e32 v12, 0xbfb8aa3b, v8
	v_mul_f32_e32 v13, 0xbfb8aa3b, v9
	v_exp_f32_e32 v12, v12
	v_exp_f32_e32 v13, v13
	v_add_f32_e32 v12, 1.0, v12
	v_add_f32_e32 v13, 1.0, v13
	v_rcp_f32_e32 v12, v12
	v_rcp_f32_e32 v13, v13
	s_nop 0
	v_pk_mul_f32 v[8:9], v[8:9], v[12:13]
	s_nop 0
	v_pk_mul_f32 v[8:9], v[0:1], v[8:9]
	v_pk_fma_f32 v[0:1], v[10:11], v[16:17], v[38:39] op_sel_hi:[1,0,1]
	s_nop 0
	v_mul_f32_e32 v10, 0xbfb8aa3b, v0
	v_mul_f32_e32 v11, 0xbfb8aa3b, v1
	v_exp_f32_e32 v10, v10
	v_exp_f32_e32 v11, v11
	v_add_f32_e32 v10, 1.0, v10
	v_add_f32_e32 v11, 1.0, v11
	v_rcp_f32_e32 v10, v10
	v_rcp_f32_e32 v11, v11
	s_nop 0
	v_pk_mul_f32 v[0:1], v[0:1], v[10:11]
	s_nop 0
	v_pk_mul_f32 v[10:11], v[2:3], v[0:1]
	v_cvt_pk_bf16_f32 v0, v4, v5
	v_mad_i64_i32 v[4:5], s[4:5], v17, s12, v[134:135]
	v_cvt_pk_bf16_f32 v1, v6, v7
	v_cvt_pk_bf16_f32 v2, v8, v9
	v_cvt_pk_bf16_f32 v3, v10, v11
	v_lshl_add_u64 v[4:5], v[4:5], 0, v[136:137]
	global_store_dwordx4 v[4:5], v[0:3], off
	s_cbranch_vccnz .LBB0_900
	s_andn2_b64 vcc, exec, s[0:1]
	s_cbranch_vccnz .LBB0_899
	s_barrier
	s_branch .LBB0_899
